# phase 1 sample sequences: the four serialised token loads per channel (each behind a vmcnt(0) that also waited for store acks) issued together ahead of the context-copy stores; counted waits
# speedup vs baseline: 1.0017x; 1.0017x over previous
; #define LAS __attribute__((address_space(3)))
; __device__ __forceinline__ unsigned f2bf(float f) { unsigned u = __builtin_bit_cast(unsigned, f); return (u + 0x7fffu + ((u >> 16) & 1u)) >> 16; }
; template <int W>
; __device__ __forceinline__ void pool_sample(const float* xs, const float* ctx, const LAS float* rs, float g, int c, int b, bf16_t* P, float* pool_s) {
;     float hist[16];
; #pragma unroll
;     for (int i = 0; i < 15; ++i) hist[i] = ctx[(size_t)(b * PCTX + i) * D + c];
;     hist[15] = 0.f;
; #pragma unroll
;     for (int i = 0; i < 11; ++i) pool_s[(size_t)(b * PCTX + i) * D + c] = hist[i + 4];
; #pragma unroll
;     for (int t = 0; t < 4; ++t) { const float h = xs[(size_t)(b * NST + t) * D + c] * rs[t] * g; hist[(15 + t) & 15] = h; float s = 0.f;
; #pragma unroll
;         for (int k = 0; k < W; ++k) s += hist[(15 + t - k) & 15];
;         P[(size_t)(MP + b * NST + t) * D + c] = (bf16_t)f2bf(s * (1.0f / W) - h);
;         pool_s[(size_t)(b * PCTX + 11 + t) * D + c] = h; }
; }
; __device__ __forceinline__ void phase1(KAP a, LAS unsigned char* lds, int tid) {
;     ...
;             for (int half = 0; half < 2; ++half) { const int c = half * 512 + tid, grp = c >> 8; const float g = a->in[5][c];
;                 if (grp == 0) pool_sample<2>(a->in[1], a->in[2], rs, g, c, b, P, a->out + O_POOLS); else if (grp == 1) pool_sample<4>(a->in[1], a->in[2], rs, g, c, b, P, a->out + O_POOLS);
.LBB0_78:
	s_load_dwordx2 s[8:9], s[16:17], 0x28
	v_add_u32_e32 v0, s0, v126
	s_waitcnt lgkmcnt(0)
	v_ashrrev_i32_e32 v1, 31, v0
	s_movk_i32 s0, 0xff
	v_cmp_lt_u32_e32 vcc, s0, v0
	v_lshl_add_u64 v[2:3], v[0:1], 2, s[8:9]
	global_load_dword v6, v[2:3], off
	s_and_saveexec_b64 s[0:1], vcc
	s_xor_b64 s[78:79], exec, s[0:1]
	s_cbranch_execz .LBB0_90
	s_load_dwordx4 s[12:15], s[16:17], 0x8
	s_load_dwordx2 s[80:81], s[16:17], 0x98
	v_ashrrev_i32_e32 v9, 8, v0
	v_cmp_lt_i32_e32 vcc, 1, v9
	s_mov_b64 s[82:83], 0
	s_waitcnt lgkmcnt(0)
	v_mov_b32_e32 v2, s14
	v_mov_b32_e32 v3, s15
	s_add_u32 s14, s80, 0x4278000
	s_addc_u32 s15, s81, 0
	v_lshl_add_u64 v[2:3], v[0:1], 2, v[2:3]
	s_mov_b64 s[86:87], 0
	s_and_saveexec_b64 s[0:1], vcc
	s_xor_b64 s[84:85], exec, s[0:1]
	s_cbranch_execz .LBB0_85
	v_cmp_eq_u32_e32 vcc, 2, v9
	s_mov_b64 s[88:89], -1
	s_and_saveexec_b64 s[86:87], vcc
	s_cbranch_execz .LBB0_82
	v_lshl_add_u64 v[4:5], s[18:19], 2, v[2:3]
	v_lshl_add_u64 v[8:9], s[30:31], 2, v[2:3]
	v_lshl_add_u64 v[10:11], s[34:35], 2, v[2:3]
	v_lshl_add_u64 v[12:13], s[36:37], 2, v[2:3]
	v_lshl_add_u64 v[14:15], s[38:39], 2, v[2:3]
	s_waitcnt vmcnt(1)
	v_lshl_add_u64 v[28:29], s[40:41], 2, v[2:3]
	v_lshl_add_u64 v[30:31], s[42:43], 2, v[2:3]
	v_lshl_add_u64 v[32:33], s[44:45], 2, v[2:3]
	global_load_dword v7, v[4:5], off
	global_load_dword v17, v[8:9], off
	global_load_dword v34, v[10:11], off
	global_load_dword v35, v[12:13], off
	global_load_dword v36, v[14:15], off
	global_load_dword v37, v[28:29], off
	global_load_dword v38, v[30:31], off
	global_load_dword v39, v[32:33], off
	v_lshl_add_u64 v[4:5], s[46:47], 2, v[2:3]
	v_lshl_add_u64 v[8:9], s[48:49], 2, v[2:3]
	v_lshl_add_u64 v[10:11], s[50:51], 2, v[2:3]
	global_load_dword v40, v[4:5], off
	global_load_dword v41, v[8:9], off
	global_load_dword v42, v[10:11], off
	v_lshlrev_b64 v[4:5], 2, v[0:1]
	v_lshl_add_u64 v[8:9], s[14:15], 0, v[4:5]
	v_lshl_add_u64 v[12:13], s[28:29], 2, v[8:9]
	v_add_co_u32_e32 v10, vcc, s94, v12
	v_lshl_add_u64 v[4:5], s[12:13], 0, v[4:5]
	s_nop 0
	v_addc_co_u32_e32 v11, vcc, 0, v13, vcc
	v_add_co_u32_e32 v14, vcc, s95, v12
	v_lshl_add_u64 v[8:9], s[58:59], 2, v[4:5]
	s_nop 0
	v_addc_co_u32_e32 v15, vcc, 0, v13, vcc
	v_add_co_u32_e32 v28, vcc, s96, v12
	s_add_i32 s0, 0, 0x20000
	s_nop 0
	v_addc_co_u32_e32 v29, vcc, 0, v13, vcc
	v_add_co_u32_e32 v30, vcc, s97, v12
	s_xor_b64 s[88:89], exec, -1
	s_nop 0
	v_addc_co_u32_e32 v31, vcc, 0, v13, vcc
	v_add_co_u32_e32 v32, vcc, s4, v12
	s_nop 1
	v_addc_co_u32_e32 v33, vcc, 0, v13, vcc
	v_lshl_add_u64 v[248:249], s[58:59], 2, v[4:5]
	global_load_dword v240, v[248:249], off
	v_lshl_add_u64 v[248:249], s[64:65], 2, v[4:5]
	global_load_dword v241, v[248:249], off
	v_lshl_add_u64 v[248:249], s[68:69], 2, v[4:5]
	global_load_dword v242, v[248:249], off
	v_lshl_add_u64 v[248:249], s[72:73], 2, v[4:5]
	global_load_dword v243, v[248:249], off
	s_waitcnt vmcnt(14)
	global_store_dword v[12:13], v7, off
	s_waitcnt vmcnt(14)
	global_store_dword v[10:11], v17, off offset:-4096
	s_waitcnt vmcnt(14)
	global_store_dword v[10:11], v34, off
	s_waitcnt vmcnt(14)
	global_store_dword v[14:15], v35, off offset:-4096
	s_waitcnt vmcnt(14)
	global_store_dword v[14:15], v36, off
	s_waitcnt vmcnt(14)
	global_store_dword v[28:29], v37, off offset:-4096
	s_waitcnt vmcnt(14)
	global_store_dword v[28:29], v38, off
	s_waitcnt vmcnt(14)
	global_store_dword v[30:31], v39, off offset:-4096
	s_waitcnt vmcnt(14)
	global_store_dword v[30:31], v40, off
	s_waitcnt vmcnt(14)
	global_store_dword v[32:33], v41, off offset:-4096
	s_waitcnt vmcnt(14)
	global_store_dword v[32:33], v42, off
	v_mov_b32_e32 v8, s0
	ds_read_b128 v[8:11], v8
	v_add_co_u32_e32 v28, vcc, s60, v12
	v_lshl_add_u64 v[14:15], s[64:65], 2, v[4:5]
	s_nop 0
	v_addc_co_u32_e32 v29, vcc, 0, v13, vcc
	s_waitcnt vmcnt(14) lgkmcnt(0)
	v_mul_f32_e32 v17, v240, v8
	v_mul_f32_e32 v7, v6, v17
	global_store_dword v[28:29], v7, off offset:-4096
	v_lshl_add_u64 v[14:15], s[68:69], 2, v[4:5]
	v_lshl_add_u64 v[4:5], s[72:73], 2, v[4:5]
	s_waitcnt vmcnt(14)
	v_mul_f32_e32 v30, v241, v9
	v_mul_f32_e32 v31, v6, v30
	global_store_dword v[28:29], v31, off
	v_add_co_u32_e32 v8, vcc, s61, v12
	v_fma_f32 v28, v6, v17, 0
	s_nop 0
	v_addc_co_u32_e32 v9, vcc, 0, v13, vcc
	v_add_f32_e32 v28, v42, v28
	v_add_f32_e32 v28, v41, v28
	v_add_f32_e32 v28, v40, v28
	v_add_f32_e32 v28, v39, v28
	v_add_f32_e32 v28, v38, v28
	v_add_f32_e32 v28, v37, v28
	v_add_f32_e32 v28, v36, v28
	v_fma_f32 v7, v28, s22, -v7
	v_bfe_u32 v28, v7, 16, 1
	v_add3_u32 v7, v7, v28, s5
	s_waitcnt vmcnt(14)
	v_mul_f32_e32 v10, v242, v10
	v_mul_f32_e32 v14, v6, v10
	global_store_dword v[8:9], v14, off
	v_lshlrev_b64 v[4:5], 1, v[0:1]
	v_lshl_add_u64 v[8:9], s[62:63], 0, v[4:5]
	global_store_short_d16_hi v[8:9], v7, off
	v_fma_f32 v7, v6, v30, 0
	v_fmac_f32_e32 v7, v6, v17
	v_add_f32_e32 v7, v42, v7
	v_add_f32_e32 v7, v41, v7
	v_add_f32_e32 v7, v40, v7
	v_add_f32_e32 v7, v39, v7
	v_add_f32_e32 v7, v38, v7
	v_add_f32_e32 v7, v37, v7
	v_fma_f32 v7, v7, s22, -v31
	v_bfe_u32 v8, v7, 16, 1
	v_lshl_add_u64 v[12:13], s[66:67], 0, v[4:5]
	v_add3_u32 v7, v7, v8, s5
	global_store_short_d16_hi v[12:13], v7, off
	v_fma_f32 v7, v6, v10, 0
	v_fmac_f32_e32 v7, v6, v30
	v_fmac_f32_e32 v7, v6, v17
	v_add_f32_e32 v7, v42, v7
	v_add_f32_e32 v7, v41, v7
	v_add_f32_e32 v7, v40, v7
	v_add_f32_e32 v7, v39, v7
	v_add_f32_e32 v7, v38, v7
	v_fma_f32 v7, v7, s22, -v14
	v_bfe_u32 v8, v7, 16, 1
	v_lshl_add_u64 v[4:5], s[70:71], 0, v[4:5]
	v_add3_u32 v7, v7, v8, s5
	global_store_short_d16_hi v[4:5], v7, off
	s_waitcnt vmcnt(17)
	v_mul_f32_e32 v4, v243, v11
	v_mul_f32_e32 v7, v6, v4
	v_fma_f32 v4, v6, v4, 0
	v_fmac_f32_e32 v4, v6, v10
	v_fmac_f32_e32 v4, v6, v30
	v_fmac_f32_e32 v4, v6, v17
	v_add_f32_e32 v4, v42, v4
	v_add_f32_e32 v4, v41, v4
	v_add_f32_e32 v4, v40, v4
	v_add_f32_e32 v4, v39, v4
	v_fma_f32 v8, v4, s22, -v7

; #define LAS __attribute__((address_space(3)))
; __device__ __forceinline__ unsigned f2bf(float f) { unsigned u = __builtin_bit_cast(unsigned, f); return (u + 0x7fffu + ((u >> 16) & 1u)) >> 16; }
; template <int W>
; __device__ __forceinline__ void pool_sample(const float* xs, const float* ctx, const LAS float* rs, float g, int c, int b, bf16_t* P, float* pool_s) {
;     float hist[16];
; #pragma unroll
;     for (int i = 0; i < 15; ++i) hist[i] = ctx[(size_t)(b * PCTX + i) * D + c];
;     hist[15] = 0.f;
; #pragma unroll
;     for (int i = 0; i < 11; ++i) pool_s[(size_t)(b * PCTX + i) * D + c] = hist[i + 4];
; #pragma unroll
;     for (int t = 0; t < 4; ++t) { const float h = xs[(size_t)(b * NST + t) * D + c] * rs[t] * g; hist[(15 + t) & 15] = h; float s = 0.f;
; #pragma unroll
;         for (int k = 0; k < W; ++k) s += hist[(15 + t - k) & 15];
;         P[(size_t)(MP + b * NST + t) * D + c] = (bf16_t)f2bf(s * (1.0f / W) - h);
;         pool_s[(size_t)(b * PCTX + 11 + t) * D + c] = h; }
; }
.LBB0_84:
	s_lshl_b64 s[86:87], s[28:29], 2
	v_lshl_add_u64 v[8:9], v[2:3], 0, s[86:87]
	v_add_co_u32_e32 v10, vcc, 0x1000, v8
	s_add_i32 s0, 0, 0x20000
	s_nop 0
	v_addc_co_u32_e32 v11, vcc, 0, v9, vcc
	v_add_co_u32_e32 v12, vcc, 0x2000, v8
	s_andn2_b64 s[82:83], s[82:83], exec
	s_nop 0
	v_addc_co_u32_e32 v13, vcc, 0, v9, vcc
	v_add_co_u32_e32 v14, vcc, 0x3000, v8
	s_nop 1
	v_addc_co_u32_e32 v15, vcc, 0, v9, vcc
	s_waitcnt vmcnt(1)
	v_add_co_u32_e32 v28, vcc, 0x4000, v8
	s_nop 1
	v_addc_co_u32_e32 v29, vcc, 0, v9, vcc
	v_add_co_u32_e32 v30, vcc, 0x5000, v8
	s_nop 1
	v_addc_co_u32_e32 v31, vcc, 0, v9, vcc
	v_add_co_u32_e32 v32, vcc, 0x6000, v8
	s_nop 1
	v_addc_co_u32_e32 v33, vcc, 0, v9, vcc
	v_add_co_u32_e32 v34, vcc, 0x7000, v8
	s_nop 1
	v_addc_co_u32_e32 v35, vcc, 0, v9, vcc
	global_load_dword v17, v[28:29], off
	global_load_dword v36, v[30:31], off
	global_load_dword v37, v[32:33], off
	global_load_dword v38, v[34:35], off
	v_add_co_u32_e32 v28, vcc, 0x8000, v8
	s_nop 1
	v_addc_co_u32_e32 v29, vcc, 0, v9, vcc
	global_load_dword v39, v[28:29], off
	v_add_co_u32_e32 v28, vcc, 0x9000, v8
	s_nop 1
	v_addc_co_u32_e32 v29, vcc, 0, v9, vcc
	v_add_co_u32_e32 v30, vcc, 0xa000, v8
	s_nop 1
	v_addc_co_u32_e32 v31, vcc, 0, v9, vcc
	v_add_co_u32_e32 v32, vcc, 0xb000, v8
	s_nop 1
	v_addc_co_u32_e32 v33, vcc, 0, v9, vcc
	v_add_co_u32_e32 v34, vcc, 0xc000, v8
	s_nop 1
	v_addc_co_u32_e32 v35, vcc, 0, v9, vcc
	global_load_dword v40, v[28:29], off
	global_load_dword v41, v[30:31], off
	s_nop 0
	global_load_dword v32, v[32:33], off
	s_nop 0
	global_load_dword v33, v[34:35], off
	v_add_co_u32_e32 v28, vcc, 0xd000, v8
	s_nop 1
	v_addc_co_u32_e32 v29, vcc, 0, v9, vcc
	v_add_co_u32_e32 v30, vcc, 0xe000, v8
	s_nop 1
	v_addc_co_u32_e32 v31, vcc, 0, v9, vcc
	global_load_dword v34, v[28:29], off
	global_load_dword v35, v[30:31], off
	global_load_dword v7, v[8:9], off
	global_load_dword v42, v[10:11], off
	global_load_dword v43, v[12:13], off
	global_load_dword v44, v[14:15], off
	v_lshlrev_b64 v[8:9], 2, v[0:1]
	v_lshl_add_u64 v[10:11], s[14:15], 0, v[8:9]
	v_lshl_add_u64 v[12:13], v[10:11], 0, s[86:87]
	v_add_co_u32_e32 v10, vcc, s94, v12
	v_lshl_add_u64 v[14:15], s[12:13], 0, v[8:9]
	s_nop 0
	v_addc_co_u32_e32 v11, vcc, 0, v13, vcc
	v_lshl_add_u64 v[8:9], s[58:59], 2, v[14:15]
	v_lshl_add_u64 v[28:29], s[64:65], 2, v[14:15]
	v_lshl_add_u64 v[248:249], s[58:59], 2, v[14:15]
	global_load_dword v240, v[248:249], off
	v_lshl_add_u64 v[248:249], s[64:65], 2, v[14:15]
	global_load_dword v241, v[248:249], off
	v_lshl_add_u64 v[248:249], s[68:69], 2, v[14:15]
	global_load_dword v242, v[248:249], off
	v_lshl_add_u64 v[248:249], s[72:73], 2, v[14:15]
	global_load_dword v243, v[248:249], off
	s_waitcnt vmcnt(18)
	global_store_dword v[12:13], v17, off
	s_waitcnt vmcnt(18)
	global_store_dword v[10:11], v36, off offset:-4096
	s_waitcnt vmcnt(18)
	global_store_dword v[10:11], v37, off
	v_add_co_u32_e32 v10, vcc, s95, v12
	s_nop 1
	v_addc_co_u32_e32 v11, vcc, 0, v13, vcc
	s_waitcnt vmcnt(18)
	global_store_dword v[10:11], v38, off offset:-4096
	s_waitcnt vmcnt(18)
	global_store_dword v[10:11], v39, off
	v_add_co_u32_e32 v10, vcc, s96, v12
	s_nop 1
	v_addc_co_u32_e32 v11, vcc, 0, v13, vcc
	s_waitcnt vmcnt(18)
	global_store_dword v[10:11], v40, off offset:-4096
	s_waitcnt vmcnt(18)
	global_store_dword v[10:11], v41, off
	v_add_co_u32_e32 v10, vcc, s97, v12
	s_nop 1
	v_addc_co_u32_e32 v11, vcc, 0, v13, vcc
	s_waitcnt vmcnt(18)
	global_store_dword v[10:11], v32, off offset:-4096
	s_waitcnt vmcnt(18)
	global_store_dword v[10:11], v33, off
	v_add_co_u32_e32 v10, vcc, s4, v12
	s_nop 1
	v_addc_co_u32_e32 v11, vcc, 0, v13, vcc
	s_waitcnt vmcnt(18)
	global_store_dword v[10:11], v34, off offset:-4096
	s_waitcnt vmcnt(18)
	global_store_dword v[10:11], v35, off
	v_mov_b32_e32 v8, s0
	ds_read_b128 v[8:11], v8
	v_add_co_u32_e32 v30, vcc, s60, v12
	s_waitcnt vmcnt(14) lgkmcnt(0)
	v_mul_f32_e32 v45, v240, v8
	v_addc_co_u32_e32 v31, vcc, 0, v13, vcc
	v_mul_f32_e32 v46, v6, v45
	global_store_dword v[30:31], v46, off offset:-4096
	v_lshl_add_u64 v[28:29], s[68:69], 2, v[14:15]
	v_add_co_u32_e32 v12, vcc, s61, v12
	s_waitcnt vmcnt(14)
	v_mul_f32_e32 v47, v241, v9
	v_mul_f32_e32 v48, v6, v47
	global_store_dword v[30:31], v48, off
	v_addc_co_u32_e32 v13, vcc, 0, v13, vcc
	v_lshl_add_u64 v[8:9], s[72:73], 2, v[14:15]
	v_fma_f32 v30, v6, v45, 0
	v_add_f32_e32 v30, v35, v30
	v_add_f32_e32 v30, v34, v30
	v_add_f32_e32 v30, v33, v30
	v_add_f32_e32 v30, v32, v30
	v_add_f32_e32 v30, v41, v30
	v_add_f32_e32 v30, v40, v30
	v_add_f32_e32 v30, v39, v30
	v_add_f32_e32 v30, v38, v30
	v_add_f32_e32 v30, v37, v30
	v_add_f32_e32 v30, v36, v30
	v_add_f32_e32 v30, v17, v30
	v_add_f32_e32 v30, v44, v30
	v_add_f32_e32 v30, v43, v30
	v_add_f32_e32 v30, v42, v30
	v_add_f32_e32 v7, v7, v30
	v_fma_f32 v7, v7, s24, -v46
	v_bfe_u32 v30, v7, 16, 1
	v_add3_u32 v7, v7, v30, s5
	s_waitcnt vmcnt(14)
	v_mul_f32_e32 v10, v242, v10
	v_mul_f32_e32 v28, v6, v10
	global_store_dword v[12:13], v28, off
	v_lshlrev_b64 v[8:9], 1, v[0:1]
	v_lshl_add_u64 v[12:13], s[62:63], 0, v[8:9]
	global_store_short_d16_hi v[12:13], v7, off
	v_fma_f32 v7, v6, v47, 0
	v_fmac_f32_e32 v7, v6, v45
	v_add_f32_e32 v7, v35, v7
	v_add_f32_e32 v7, v34, v7
	v_add_f32_e32 v7, v33, v7
	v_add_f32_e32 v7, v32, v7
	v_add_f32_e32 v7, v41, v7
	v_add_f32_e32 v7, v40, v7
	v_add_f32_e32 v7, v39, v7
	v_add_f32_e32 v7, v38, v7
	v_add_f32_e32 v7, v37, v7
	v_add_f32_e32 v7, v36, v7
	v_add_f32_e32 v7, v17, v7
	v_add_f32_e32 v7, v44, v7
	v_add_f32_e32 v7, v43, v7
	v_add_f32_e32 v7, v42, v7
	v_fma_f32 v7, v7, s24, -v48
	v_bfe_u32 v12, v7, 16, 1
	v_lshl_add_u64 v[14:15], s[66:67], 0, v[8:9]
	v_add3_u32 v7, v7, v12, s5
	global_store_short_d16_hi v[14:15], v7, off
	v_fma_f32 v7, v6, v10, 0
	v_fmac_f32_e32 v7, v6, v47
	v_fmac_f32_e32 v7, v6, v45
	v_add_f32_e32 v7, v35, v7
	v_add_f32_e32 v7, v34, v7
	v_add_f32_e32 v7, v33, v7
	v_add_f32_e32 v7, v32, v7
	v_add_f32_e32 v7, v41, v7
	v_add_f32_e32 v7, v40, v7
	v_add_f32_e32 v7, v39, v7
	v_add_f32_e32 v7, v38, v7
	v_add_f32_e32 v7, v37, v7
	v_add_f32_e32 v7, v36, v7
	v_add_f32_e32 v7, v17, v7
	v_add_f32_e32 v7, v44, v7
	v_add_f32_e32 v7, v43, v7
	v_fma_f32 v7, v7, s24, -v28
	v_bfe_u32 v12, v7, 16, 1
	v_lshl_add_u64 v[8:9], s[70:71], 0, v[8:9]
	v_add3_u32 v7, v7, v12, s5
	global_store_short_d16_hi v[8:9], v7, off
	s_waitcnt vmcnt(17)
	v_mul_f32_e32 v8, v243, v11
	v_mul_f32_e32 v7, v6, v8
	v_fma_f32 v8, v6, v8, 0
	v_fmac_f32_e32 v8, v6, v10
	v_fmac_f32_e32 v8, v6, v47
	v_fmac_f32_e32 v8, v6, v45
	v_add_f32_e32 v8, v35, v8
	v_add_f32_e32 v8, v34, v8
	v_add_f32_e32 v8, v33, v8
	v_add_f32_e32 v8, v32, v8
	v_add_f32_e32 v8, v41, v8
	v_add_f32_e32 v8, v40, v8
	v_add_f32_e32 v8, v39, v8
	v_add_f32_e32 v8, v38, v8
	v_add_f32_e32 v8, v37, v8
	v_add_f32_e32 v8, v36, v8
	v_add_f32_e32 v8, v17, v8
	v_add_f32_e32 v8, v44, v8
	v_fma_f32 v8, v8, s24, -v7
	s_or_b64 exec, exec, s[84:85]
	s_and_saveexec_b64 s[84:85], s[82:83]
	s_cbranch_execnz .LBB0_88
	s_branch .LBB0_89

; #define LAS __attribute__((address_space(3)))
; __device__ __forceinline__ unsigned f2bf(float f) { unsigned u = __builtin_bit_cast(unsigned, f); return (u + 0x7fffu + ((u >> 16) & 1u)) >> 16; }
; template <int W>
; __device__ __forceinline__ void pool_sample(const float* xs, const float* ctx, const LAS float* rs, float g, int c, int b, bf16_t* P, float* pool_s) {
;     float hist[16];
; #pragma unroll
;     for (int i = 0; i < 15; ++i) hist[i] = ctx[(size_t)(b * PCTX + i) * D + c];
;     hist[15] = 0.f;
; #pragma unroll
;     for (int i = 0; i < 11; ++i) pool_s[(size_t)(b * PCTX + i) * D + c] = hist[i + 4];
; #pragma unroll
;     for (int t = 0; t < 4; ++t) { const float h = xs[(size_t)(b * NST + t) * D + c] * rs[t] * g; hist[(15 + t) & 15] = h; float s = 0.f;
; #pragma unroll
;         for (int k = 0; k < W; ++k) s += hist[(15 + t - k) & 15];
;         P[(size_t)(MP + b * NST + t) * D + c] = (bf16_t)f2bf(s * (1.0f / W) - h);
;         pool_s[(size_t)(b * PCTX + 11 + t) * D + c] = h; }
; }
.LBB0_88:
	v_lshl_add_u64 v[4:5], s[18:19], 2, v[2:3]
	v_lshl_add_u64 v[32:33], s[44:45], 2, v[2:3]
	v_lshl_add_u64 v[8:9], s[30:31], 2, v[2:3]
	v_lshl_add_u64 v[10:11], s[34:35], 2, v[2:3]
	v_lshl_add_u64 v[12:13], s[36:37], 2, v[2:3]
	v_lshl_add_u64 v[14:15], s[38:39], 2, v[2:3]
	s_waitcnt vmcnt(1)
	v_lshl_add_u64 v[28:29], s[40:41], 2, v[2:3]
	v_lshl_add_u64 v[30:31], s[42:43], 2, v[2:3]
	global_load_dword v7, v[4:5], off
	global_load_dword v17, v[8:9], off
	global_load_dword v34, v[10:11], off
	global_load_dword v35, v[12:13], off
	global_load_dword v36, v[14:15], off
	global_load_dword v37, v[28:29], off
	global_load_dword v38, v[30:31], off
	s_nop 0
	global_load_dword v32, v[32:33], off
	v_lshl_add_u64 v[4:5], s[46:47], 2, v[2:3]
	v_lshl_add_u64 v[8:9], s[48:49], 2, v[2:3]
	v_lshl_add_u64 v[2:3], s[50:51], 2, v[2:3]
	global_load_dword v33, v[4:5], off
	global_load_dword v39, v[8:9], off
	global_load_dword v40, v[2:3], off
	v_lshlrev_b64 v[2:3], 2, v[0:1]
	v_lshl_add_u64 v[4:5], s[14:15], 0, v[2:3]
	v_lshl_add_u64 v[10:11], s[28:29], 2, v[4:5]
	v_add_co_u32_e32 v4, vcc, s94, v10
	v_lshl_add_u64 v[8:9], s[12:13], 0, v[2:3]
	s_nop 0
	v_addc_co_u32_e32 v5, vcc, 0, v11, vcc
	v_add_co_u32_e32 v12, vcc, s95, v10
	v_lshl_add_u64 v[2:3], s[58:59], 2, v[8:9]
	s_nop 0
	v_addc_co_u32_e32 v13, vcc, 0, v11, vcc
	v_add_co_u32_e32 v14, vcc, s96, v10
	s_add_i32 s0, 0, 0x20000
	s_nop 0
	v_addc_co_u32_e32 v15, vcc, 0, v11, vcc
	v_add_co_u32_e32 v28, vcc, s97, v10
	s_nop 1
	v_addc_co_u32_e32 v29, vcc, 0, v11, vcc
	v_add_co_u32_e32 v30, vcc, s4, v10
	s_nop 1
	v_addc_co_u32_e32 v31, vcc, 0, v11, vcc
	v_lshl_add_u64 v[248:249], s[58:59], 2, v[8:9]
	global_load_dword v240, v[248:249], off
	v_lshl_add_u64 v[248:249], s[64:65], 2, v[8:9]
	global_load_dword v241, v[248:249], off
	v_lshl_add_u64 v[248:249], s[68:69], 2, v[8:9]
	global_load_dword v242, v[248:249], off
	v_lshl_add_u64 v[248:249], s[72:73], 2, v[8:9]
	global_load_dword v243, v[248:249], off
	s_waitcnt vmcnt(14)
	global_store_dword v[10:11], v7, off
	s_waitcnt vmcnt(14)
	global_store_dword v[4:5], v17, off offset:-4096
	s_waitcnt vmcnt(14)
	global_store_dword v[4:5], v34, off
	s_waitcnt vmcnt(14)
	global_store_dword v[12:13], v35, off offset:-4096
	s_waitcnt vmcnt(14)
	global_store_dword v[12:13], v36, off
	s_waitcnt vmcnt(14)
	global_store_dword v[14:15], v37, off offset:-4096
	s_waitcnt vmcnt(14)
	global_store_dword v[14:15], v38, off
	s_waitcnt vmcnt(14)
	global_store_dword v[28:29], v32, off offset:-4096
	s_waitcnt vmcnt(14)
	global_store_dword v[28:29], v33, off
	s_waitcnt vmcnt(14)
	global_store_dword v[30:31], v39, off offset:-4096
	s_waitcnt vmcnt(14)
	global_store_dword v[30:31], v40, off
	v_mov_b32_e32 v2, s0
	ds_read_b128 v[2:5], v2
	v_add_co_u32_e32 v14, vcc, s60, v10
	v_lshl_add_u64 v[12:13], s[64:65], 2, v[8:9]
	s_nop 0
	v_addc_co_u32_e32 v15, vcc, 0, v11, vcc
	s_waitcnt vmcnt(14) lgkmcnt(0)
	v_mul_f32_e32 v17, v240, v2
	v_mul_f32_e32 v7, v6, v17
	global_store_dword v[14:15], v7, off offset:-4096
	v_lshl_add_u64 v[12:13], s[68:69], 2, v[8:9]
	s_waitcnt vmcnt(14)
	v_mul_f32_e32 v28, v241, v3
	v_mul_f32_e32 v29, v6, v28
	global_store_dword v[14:15], v29, off
	v_lshl_add_u64 v[2:3], s[72:73], 2, v[8:9]
	v_add_co_u32_e32 v8, vcc, 0xd000, v10
	v_fma_f32 v14, v6, v17, 0
	s_nop 0
	v_addc_co_u32_e32 v9, vcc, 0, v11, vcc
	v_add_f32_e32 v14, v40, v14
	v_add_f32_e32 v14, v39, v14
	v_add_f32_e32 v14, v33, v14
	v_fma_f32 v7, v14, s26, -v7
	v_bfe_u32 v14, v7, 16, 1
	v_add3_u32 v7, v7, v14, s5
	s_waitcnt vmcnt(14)
	v_mul_f32_e32 v4, v242, v4
	v_mul_f32_e32 v12, v6, v4
	global_store_dword v[8:9], v12, off
	v_lshlrev_b64 v[2:3], 1, v[0:1]
	v_lshl_add_u64 v[8:9], s[62:63], 0, v[2:3]
	global_store_short_d16_hi v[8:9], v7, off
	v_fma_f32 v7, v6, v28, 0
	v_fmac_f32_e32 v7, v6, v17
	v_add_f32_e32 v7, v40, v7
	v_add_f32_e32 v7, v39, v7
	v_fma_f32 v7, v7, s26, -v29
	v_bfe_u32 v8, v7, 16, 1
	v_lshl_add_u64 v[10:11], s[66:67], 0, v[2:3]
	v_add3_u32 v7, v7, v8, s5
	global_store_short_d16_hi v[10:11], v7, off
	v_fma_f32 v7, v6, v4, 0
	v_fmac_f32_e32 v7, v6, v28
	v_fmac_f32_e32 v7, v6, v17
	v_add_f32_e32 v7, v40, v7
	v_fma_f32 v7, v7, s26, -v12
	v_bfe_u32 v8, v7, 16, 1
	v_lshl_add_u64 v[2:3], s[70:71], 0, v[2:3]
	v_add3_u32 v7, v7, v8, s5
	global_store_short_d16_hi v[2:3], v7, off
	s_waitcnt vmcnt(17)
	v_mul_f32_e32 v2, v243, v5
	v_mul_f32_e32 v7, v6, v2
	v_fma_f32 v2, v6, v2, 0
	v_fmac_f32_e32 v2, v6, v4
	v_fmac_f32_e32 v2, v6, v28
	v_fmac_f32_e32 v2, v6, v17
	v_fma_f32 v8, v2, s26, -v7
	v_mov_b64_e32 v[4:5], s[80:81]

; #define LAS __attribute__((address_space(3)))
; __device__ __forceinline__ unsigned f2bf(float f) { unsigned u = __builtin_bit_cast(unsigned, f); return (u + 0x7fffu + ((u >> 16) & 1u)) >> 16; }
; #define LDS_SYNC() do { asm volatile("s_waitcnt lgkmcnt(0)" ::: "memory"); __builtin_amdgcn_s_barrier(); asm volatile("" ::: "memory"); } while (0)
; template <int W>
; __device__ __forceinline__ void pool_sample(const float* xs, const float* ctx, const LAS float* rs, float g, int c, int b, bf16_t* P, float* pool_s) {
;     float hist[16];
; #pragma unroll
;     for (int i = 0; i < 15; ++i) hist[i] = ctx[(size_t)(b * PCTX + i) * D + c];
;     hist[15] = 0.f;
; #pragma unroll
;     for (int i = 0; i < 11; ++i) pool_s[(size_t)(b * PCTX + i) * D + c] = hist[i + 4];
; #pragma unroll
;     for (int t = 0; t < 4; ++t) { const float h = xs[(size_t)(b * NST + t) * D + c] * rs[t] * g; hist[(15 + t) & 15] = h; float s = 0.f;
; #pragma unroll
;         for (int k = 0; k < W; ++k) s += hist[(15 + t - k) & 15];
;         P[(size_t)(MP + b * NST + t) * D + c] = (bf16_t)f2bf(s * (1.0f / W) - h);
;         pool_s[(size_t)(b * PCTX + 11 + t) * D + c] = h; }
; }
; __device__ __forceinline__ void phase1(KAP a, LAS unsigned char* lds, int tid) {
;     ...
;         } else { const int b = it - 256;
;             if (wave < 4) { const float* rp[1] = {a->in[1] + (size_t)(b * NST + wave) * D}; float o[1]; rows_rstd<1>(rp, o, lane); if (lane == 0) rs[wave] = o[0]; }
;             LDS_SYNC();
; #pragma unroll 1
;             for (int half = 0; half < 2; ++half) { const int c = half * 512 + tid, grp = c >> 8; const float g = a->in[5][c];
;                 if (grp == 0) pool_sample<2>(a->in[1], a->in[2], rs, g, c, b, P, a->out + O_POOLS); else if (grp == 1) pool_sample<4>(a->in[1], a->in[2], rs, g, c, b, P, a->out + O_POOLS);
;                 else if (grp == 2) pool_sample<8>(a->in[1], a->in[2], rs, g, c, b, P, a->out + O_POOLS); else pool_sample<16>(a->in[1], a->in[2], rs, g, c, b, P, a->out + O_POOLS); }
.LBB0_90:
	s_andn2_saveexec_b64 s[78:79], s[78:79]
	s_cbranch_execz .LBB0_77
	s_load_dwordx4 s[12:15], s[16:17], 0x8
	s_load_dwordx2 s[80:81], s[16:17], 0x98
	v_lshlrev_b64 v[2:3], 2, v[0:1]
	s_mov_b32 s0, 0x4279000
	s_mov_b32 s1, 0x427b000
	s_waitcnt lgkmcnt(0)
	v_lshl_add_u64 v[4:5], s[14:15], 0, v[2:3]
	v_lshl_add_u64 v[8:9], s[18:19], 2, v[4:5]
	v_lshl_add_u64 v[34:35], s[44:45], 2, v[4:5]
	v_lshl_add_u64 v[10:11], s[30:31], 2, v[4:5]
	v_lshl_add_u64 v[12:13], s[34:35], 2, v[4:5]
	v_lshl_add_u64 v[14:15], s[36:37], 2, v[4:5]
	s_waitcnt vmcnt(1)
	v_lshl_add_u64 v[28:29], s[38:39], 2, v[4:5]
	v_lshl_add_u64 v[30:31], s[40:41], 2, v[4:5]
	v_lshl_add_u64 v[32:33], s[42:43], 2, v[4:5]
	global_load_dword v7, v[8:9], off
	global_load_dword v17, v[10:11], off
	global_load_dword v36, v[12:13], off
	global_load_dword v37, v[14:15], off
	global_load_dword v38, v[28:29], off
	global_load_dword v39, v[30:31], off
	global_load_dword v40, v[32:33], off
	s_nop 0
	global_load_dword v34, v[34:35], off
	v_lshl_add_u64 v[8:9], s[46:47], 2, v[4:5]
	v_lshl_add_u64 v[10:11], s[48:49], 2, v[4:5]
	v_lshl_add_u64 v[4:5], s[50:51], 2, v[4:5]
	global_load_dword v35, v[8:9], off
	global_load_dword v41, v[10:11], off
	global_load_dword v42, v[4:5], off
	v_lshl_add_u64 v[4:5], s[80:81], 0, v[2:3]
	v_lshl_add_u64 v[10:11], s[28:29], 2, v[4:5]
	v_add_co_u32_e32 v4, vcc, s0, v10
	s_mov_b32 s8, 0x427d000
	s_nop 0
	v_addc_co_u32_e32 v5, vcc, 0, v11, vcc
	v_add_co_u32_e32 v12, vcc, s1, v10
	s_mov_b32 s9, 0x427f000
	s_nop 0
	v_addc_co_u32_e32 v13, vcc, 0, v11, vcc
	v_add_co_u32_e32 v14, vcc, s8, v10
	s_mov_b32 s10, 0x4281000
	s_nop 0
	v_addc_co_u32_e32 v15, vcc, 0, v11, vcc
	v_add_co_u32_e32 v28, vcc, s9, v10
	s_mov_b32 s11, 0x4283000
	s_nop 0
	v_addc_co_u32_e32 v29, vcc, 0, v11, vcc
	v_add_co_u32_e32 v30, vcc, s10, v10
	v_lshl_add_u64 v[8:9], s[12:13], 0, v[2:3]
	s_nop 0
	v_addc_co_u32_e32 v31, vcc, 0, v11, vcc
	v_add_co_u32_e32 v32, vcc, s11, v10
	v_lshl_add_u64 v[2:3], s[58:59], 2, v[8:9]
	s_nop 0
	v_addc_co_u32_e32 v33, vcc, 0, v11, vcc
	s_add_i32 s0, 0, 0x20000
	v_lshl_add_u64 v[248:249], s[58:59], 2, v[8:9]
	global_load_dword v240, v[248:249], off
	v_lshl_add_u64 v[248:249], s[64:65], 2, v[8:9]
	global_load_dword v241, v[248:249], off
	v_lshl_add_u64 v[248:249], s[68:69], 2, v[8:9]
	global_load_dword v242, v[248:249], off
	v_lshl_add_u64 v[248:249], s[72:73], 2, v[8:9]
	global_load_dword v243, v[248:249], off
	s_waitcnt vmcnt(14)
	global_store_dword v[4:5], v7, off offset:-4096
	s_waitcnt vmcnt(14)
	global_store_dword v[4:5], v17, off
	s_waitcnt vmcnt(14)
	global_store_dword v[12:13], v36, off offset:-4096
	s_waitcnt vmcnt(14)
	global_store_dword v[12:13], v37, off
	s_waitcnt vmcnt(14)
	global_store_dword v[14:15], v38, off offset:-4096
	s_waitcnt vmcnt(14)
	global_store_dword v[14:15], v39, off
	s_waitcnt vmcnt(14)
	global_store_dword v[28:29], v40, off offset:-4096
	s_waitcnt vmcnt(14)
	global_store_dword v[28:29], v34, off
	s_waitcnt vmcnt(14)
	global_store_dword v[30:31], v35, off offset:-4096
	s_waitcnt vmcnt(14)
	global_store_dword v[30:31], v41, off
	s_waitcnt vmcnt(14)
	global_store_dword v[32:33], v42, off offset:-4096
	v_mov_b32_e32 v2, s0
	ds_read_b128 v[2:5], v2
	v_lshl_add_u64 v[12:13], s[64:65], 2, v[8:9]
	s_mov_b32 s0, 0x4284000
	v_add_co_u32_e32 v14, vcc, s0, v10
	s_waitcnt vmcnt(14) lgkmcnt(0)
	v_mul_f32_e32 v7, v240, v2
	v_mul_f32_e32 v17, v6, v7
	global_store_dword v[32:33], v17, off
	v_addc_co_u32_e32 v15, vcc, 0, v11, vcc
	v_lshl_add_u64 v[12:13], s[68:69], 2, v[8:9]
	s_waitcnt vmcnt(14)
	v_mul_f32_e32 v28, v241, v3
	v_mul_f32_e32 v29, v6, v28
	global_store_dword v[14:15], v29, off
	v_lshl_add_u64 v[2:3], s[72:73], 2, v[8:9]
	v_add_co_u32_e32 v8, vcc, 0x4285000, v10
	v_fma_f32 v14, v6, v7, 0
	s_nop 0
	v_addc_co_u32_e32 v9, vcc, 0, v11, vcc
	v_add_f32_e32 v14, v42, v14
	v_fma_f32 v14, v14, 0.5, -v17
	v_bfe_u32 v15, v14, 16, 1
	v_add3_u32 v14, v14, v15, s5
	s_waitcnt vmcnt(14)
	v_mul_f32_e32 v4, v242, v4
	v_mul_f32_e32 v12, v6, v4
	global_store_dword v[8:9], v12, off
	v_lshlrev_b64 v[2:3], 1, v[0:1]
	v_lshl_add_u64 v[8:9], s[62:63], 0, v[2:3]
	global_store_short_d16_hi v[8:9], v14, off
	v_fma_f32 v8, v6, v28, 0
	v_fmac_f32_e32 v8, v6, v7
	v_fma_f32 v7, v8, 0.5, -v29
	v_bfe_u32 v8, v7, 16, 1
	v_lshl_add_u64 v[10:11], s[66:67], 0, v[2:3]
	v_add3_u32 v7, v7, v8, s5
	global_store_short_d16_hi v[10:11], v7, off
	v_fma_f32 v7, v6, v4, 0
	v_fmac_f32_e32 v7, v6, v28
	v_fma_f32 v7, v7, 0.5, -v12
	v_bfe_u32 v8, v7, 16, 1
	v_lshl_add_u64 v[2:3], s[70:71], 0, v[2:3]
	v_add3_u32 v7, v7, v8, s5
	global_store_short_d16_hi v[2:3], v7, off
	s_waitcnt vmcnt(17)
	v_mul_f32_e32 v2, v243, v5
	v_mul_f32_e32 v7, v6, v2
	v_fma_f32 v2, v6, v2, 0
	v_fmac_f32_e32 v2, v6, v4
	v_fma_f32 v8, v2, 0.5, -v7
	v_mov_b64_e32 v[4:5], s[80:81]
	s_branch .LBB0_77
